# v095 + lever 4 mirrored: static s_setprio 1 for waves 0-3 (leading half) over the P1/P3 phases, per-block flips deleted
# speedup vs baseline: 1.0040x; 1.0040x over previous
; #define PG8_STAGE(bufoff, gbase, voff) do { _Pragma("unroll") for (int _i = 0; _i < 2; ++_i) \
;         __builtin_amdgcn_global_load_lds((const unsigned*)((const char*)(gbase) + (voff)[_i]), (PG8_LAS unsigned*)(lds + (bufoff) + ldsw + _i * 8192), 16, 0, 0); } while (0)
; #define PG8_WAIT_V(n) asm volatile("s_waitcnt vmcnt(" #n ")" ::: "memory")
; #define PG8_BAR __builtin_amdgcn_s_barrier()
; template <class Epi, class Sched, bool ALIGN_EPI = false, bool SP2 = false, bool RS = false, bool BPRE = false>
; __device__ __forceinline__ void gemm_phase(PG8_LAS unsigned char* lds, const Gemm g, const Sched& S, const Epi& E, const float* rs_ss = nullptr, PG8_LAS float* rs_tab = nullptr) {
;     ...
;         PG8_WAIT_V(2); PG8_BAR;
;         PG8_STAGE(PG8_SB(1, 0), cB + kstep, voffB); PG8_STAGE(PG8_SA(1, 0), cA + kstep, voffA); PG8_STAGE(PG8_SB(1, 1), cB + hstep + kstep, voffB);
;         PG8_WAIT_V(6); PG8_BAR;
.LBB0_190:
	s_and_b32 s5, s0, 3
	s_ashr_i32 s77, s3, 31
	s_ashr_i32 s78, s2, 31
	s_lshl_b32 s12, s7, 13
	s_lshl_b32 s13, s5, 12
	s_add_u32 s0, s58, 0x4000
	s_addc_u32 s1, s59, 0
	s_add_i32 m0, s72, 0x18000
	v_lshl_add_u64 v[4:5], s[0:1], 0, v[138:139]
	s_waitcnt vmcnt(2)
	s_barrier
	global_load_lds_dwordx4 v[4:5], off
	s_add_i32 m0, s72, 0x1a000
	v_lshl_add_u64 v[4:5], s[0:1], 0, v[140:141]
	s_add_u32 s0, s56, 0x4000
	s_addc_u32 s1, s57, 0
	s_add_i32 s79, s72, 0x8000
	global_load_lds_dwordx4 v[4:5], off
	v_lshl_add_u64 v[4:5], s[0:1], 0, v[138:139]
	s_mov_b32 m0, s79
	s_add_i32 s80, s72, 0xa000
	global_load_lds_dwordx4 v[4:5], off
	v_lshl_add_u64 v[4:5], s[0:1], 0, v[140:141]
	s_add_u32 s0, s58, 0x84000
	s_mov_b32 m0, s80
	s_addc_u32 s1, s59, 0
	global_load_lds_dwordx4 v[4:5], off
	s_add_i32 m0, s72, 0x1c000
	v_lshl_add_u64 v[4:5], s[0:1], 0, v[138:139]
	global_load_lds_dwordx4 v[4:5], off
	v_lshl_add_u64 v[4:5], s[0:1], 0, v[140:141]
	s_add_i32 m0, s72, 0x1e000
	v_and_b32_e32 v6, 48, v0
	global_load_lds_dwordx4 v[4:5], off
	v_lshlrev_b32_e32 v1, 6, v0
	s_movk_i32 s0, 0x3c0
	v_and_b32_e32 v4, 15, v0
	v_and_or_b32 v7, v1, s0, v6
	v_lshlrev_b32_e32 v1, 2, v0
	v_bfe_u32 v5, v0, 4, 2
	v_and_b32_e32 v8, 32, v1
	v_lshl_or_b32 v1, s7, 6, v4
	v_lshlrev_b32_e32 v4, 6, v4
	v_or_b32_e32 v6, v4, v6
	s_waitcnt vmcnt(6)
	s_cmpk_lt_u32 s6, 0x100
	v_lshl_or_b32 v4, v5, 4, v4
	v_cmp_eq_u32_e64 s[0:1], 0, v5
	v_bitop3_b32 v6, v6, s12, v8 bitop3:0xde
	v_bitop3_b32 v160, s13, v7, v8 bitop3:0xf6
	s_cselect_b64 s[12:13], -1, 0
	s_lshl_b32 s6, s5, 1
	v_lshl_or_b32 v4, s5, 10, v4
	v_mov_b32_e32 v5, v142
	v_add_u32_e32 v146, v2, v3
	s_add_i32 s83, 0, 0x10000
	s_add_i32 s86, 0, 0x14000
	v_mbcnt_lo_u32_b32 v2, -1, 0
	s_or_b32 s81, s6, 0xffffffa0
	v_lshl_add_u64 v[144:145], s[36:37], 0, v[4:5]
	v_mov_b32_e32 v147, v142
	v_mov_b64_e32 v[148:149], 0x700
	v_mov_b64_e32 v[150:151], 0x6ff
	s_movk_i32 s82, 0xe1
	v_add_u32_e32 v161, s83, v160
	v_add_u32_e32 v162, s86, v160
	v_add_u32_e32 v163, 0, v6
	s_mov_b32 s14, 0x3db8aa3b
	v_mbcnt_hi_u32_b32 v164, -1, v2
	s_barrier
	s_cmp_ge_u32 s33, 4
	s_cbranch_scc1 .Lprio_p1
	s_setprio 1

; #define PG8_STAGE(bufoff, gbase, voff) do { _Pragma("unroll") for (int _i = 0; _i < 2; ++_i) \
;         __builtin_amdgcn_global_load_lds((const unsigned*)((const char*)(gbase) + (voff)[_i]), (PG8_LAS unsigned*)(lds + (bufoff) + ldsw + _i * 8192), 16, 0, 0); } while (0)
; #define PG8_WAIT_V(n) asm volatile("s_waitcnt vmcnt(" #n ")" ::: "memory")
; #define PG8_BAR __builtin_amdgcn_s_barrier()
; template <class Epi, class Sched, bool ALIGN_EPI = false, bool SP2 = false, bool RS = false, bool BPRE = false>
; __device__ __forceinline__ void gemm_phase(PG8_LAS unsigned char* lds, const Gemm g, const Sched& S, const Epi& E, const float* rs_ss = nullptr, PG8_LAS float* rs_tab = nullptr) {
;     ...
;         PG8_WAIT_V(2); PG8_BAR;
;         PG8_STAGE(PG8_SB(1, 0), cB + kstep, voffB); PG8_STAGE(PG8_SA(1, 0), cA + kstep, voffA); PG8_STAGE(PG8_SB(1, 1), cB + hstep + kstep, voffB);
;         PG8_WAIT_V(6); PG8_BAR;
.LBB0_738:
	s_and_b32 s59, s5, 3
	s_lshl_b32 s5, s4, 13
	s_lshl_b32 s8, s59, 12
	s_add_u32 s6, s38, 0x4000
	s_addc_u32 s7, s39, 0
	s_add_i32 m0, s55, 0x18000
	v_lshl_add_u64 v[6:7], s[6:7], 0, v[134:135]
	s_waitcnt vmcnt(2)
	s_barrier
	global_load_lds_dwordx4 v[6:7], off
	s_add_i32 m0, s55, 0x1a000
	v_lshl_add_u64 v[6:7], s[6:7], 0, v[136:137]
	s_add_u32 s6, s10, 0x4000
	s_addc_u32 s7, s11, 0
	s_add_i32 s60, s55, 0x8000
	global_load_lds_dwordx4 v[6:7], off
	v_lshl_add_u64 v[6:7], s[6:7], 0, v[134:135]
	s_mov_b32 m0, s60
	s_add_i32 s61, s55, 0xa000
	global_load_lds_dwordx4 v[6:7], off
	v_lshl_add_u64 v[6:7], s[6:7], 0, v[136:137]
	s_add_u32 s6, s38, 0xc4000
	s_mov_b32 m0, s61
	s_addc_u32 s7, s39, 0
	global_load_lds_dwordx4 v[6:7], off
	s_add_i32 m0, s55, 0x1c000
	v_lshl_add_u64 v[6:7], s[6:7], 0, v[134:135]
	global_load_lds_dwordx4 v[6:7], off
	v_lshl_add_u64 v[6:7], s[6:7], 0, v[136:137]
	s_add_i32 m0, s55, 0x1e000
	v_and_b32_e32 v5, 15, v0
	global_load_lds_dwordx4 v[6:7], off
	v_and_b32_e32 v8, 48, v0
	v_lshl_or_b32 v1, s4, 6, v5
	v_lshl_or_b32 v9, v5, 6, v8
	v_lshlrev_b32_e32 v5, 2, v5
	v_and_b32_e32 v10, 32, v5
	v_bitop3_b32 v9, v9, s5, v10 bitop3:0xde
	v_lshlrev_b32_e32 v10, 6, v0
	s_movk_i32 s5, 0x3c0
	v_and_or_b32 v8, v10, s5, v8
	s_lshl_b32 s4, s4, 8
	s_add_i32 s5, 0, 0x20000
	v_bfe_u32 v6, v0, 4, 2
	v_lshlrev_b32_e32 v10, 2, v0
	s_waitcnt vmcnt(6)
	s_add_i32 s4, s5, s4
	v_lshlrev_b32_e32 v7, 3, v6
	v_and_b32_e32 v11, 32, v10
	s_mov_b64 s[6:7], 0xc4000
	v_add_u32_e32 v151, s4, v5
	s_cmpk_lt_u32 s18, 0x100
	v_add_u32_e32 v4, v3, v4
	v_mov_b32_e32 v5, v2
	v_mbcnt_lo_u32_b32 v3, -1, 0
	v_bitop3_b32 v150, s8, v8, v11 bitop3:0xf6
	v_add_u32_e32 v152, s5, v10
	s_cselect_b64 s[18:19], -1, 0
	v_cmp_eq_u32_e64 s[8:9], 0, v6
	s_ashr_i32 s62, s3, 31
	s_ashr_i32 s63, s2, 31
	v_lshl_or_b32 v153, s59, 5, v7
	v_or_b32_e32 v138, 0xc4000, v134
	v_mov_b32_e32 v139, v135
	v_lshl_add_u64 v[140:141], v[4:5], 0, s[6:7]
	v_mov_b64_e32 v[142:143], 0x200
	v_mov_b64_e32 v[144:145], 0x1ff
	s_add_i32 s64, 0, 0x10000
	s_add_i32 s65, 0, 0x14000
	v_add_u32_e32 v154, 0, v9
	v_mov_b32_e32 v155, 0x358637bd
	s_mov_b32 s66, 0xf800000
	v_mov_b32_e32 v156, 0x260
	v_mbcnt_hi_u32_b32 v157, -1, v3
	s_mov_b32 s40, 0
	s_barrier
	s_cmp_ge_u32 s33, 4
	s_cbranch_scc1 .Lprio_p3
	s_setprio 1
